# P1 fp8 row stores widened to 16 bytes (DPP quad transpose of 4 dwords) and written through (sc1), counted vmcnt waits re-derived; on top of LN row-store write-through
# speedup vs baseline: 1.0046x; 1.0046x over previous
.LBB0_131:
	v_add_f32_e32 v130, v126, v127
	v_add_f32_e32 v134, v128, v129
	v_add_f32_e32 v130, v130, v134
	v_add_f32_e32 v134, v122, v123
	v_add_f32_e32 v135, v124, v125
	v_add_f32_e32 v130, 0, v130
	v_add_f32_e32 v134, v134, v135
	v_add_f32_e32 v130, v134, v130
	v_add_f32_e32 v134, v118, v119
	v_add_f32_e32 v135, v120, v121
	v_add_f32_e32 v134, v134, v135
	v_add_f32_e32 v130, v134, v130
	v_add_f32_e32 v134, v114, v115
	v_add_f32_e32 v135, v116, v117
	v_add_f32_e32 v134, v134, v135
	v_add_f32_e32 v130, v134, v130
	v_add_f32_e32 v134, v110, v111
	v_add_f32_e32 v135, v112, v113
	v_add_f32_e32 v134, v134, v135
	v_add_f32_e32 v130, v134, v130
	v_add_f32_e32 v134, v106, v107
	v_add_f32_e32 v135, v108, v109
	v_add_f32_e32 v134, v134, v135
	v_add_f32_e32 v130, v134, v130
	v_add_f32_e32 v134, v102, v103
	v_add_f32_e32 v135, v104, v105
	v_add_f32_e32 v134, v134, v135
	v_add_f32_e32 v130, v134, v130
	v_add_f32_e32 v134, v98, v99
	v_add_f32_e32 v135, v100, v101
	v_add_f32_e32 v134, v134, v135
	v_add_f32_e32 v130, v134, v130
	v_add_f32_e32 v134, v30, v31
	v_add_f32_e32 v135, v32, v33
	v_add_f32_e32 v134, v134, v135
	v_add_f32_e32 v130, v134, v130
	v_add_f32_e32 v134, v26, v27
	v_add_f32_e32 v135, v28, v29
	v_add_f32_e32 v134, v134, v135
	v_add_f32_e32 v130, v134, v130
	v_add_f32_e32 v134, v22, v23
	v_add_f32_e32 v135, v24, v25
	v_add_f32_e32 v134, v134, v135
	v_add_f32_e32 v130, v134, v130
	v_add_f32_e32 v134, v18, v19
	v_add_f32_e32 v135, v20, v21
	v_add_f32_e32 v134, v134, v135
	v_add_f32_e32 v130, v134, v130
	v_add_f32_e32 v134, v14, v15
	v_add_f32_e32 v135, v16, v17
	v_add_f32_e32 v134, v134, v135
	v_add_f32_e32 v130, v134, v130
	v_add_f32_e32 v134, v10, v11
	v_add_f32_e32 v135, v12, v13
	v_add_f32_e32 v134, v134, v135
	v_add_f32_e32 v130, v134, v130
	v_add_f32_e32 v134, v6, v7
	v_add_f32_e32 v135, v8, v9
	v_add_f32_e32 v134, v134, v135
	v_add_f32_e32 v130, v134, v130
	v_add_f32_e32 v134, v2, v3
	v_add_f32_e32 v135, v4, v5
	v_add_f32_e32 v134, v134, v135
	v_add_f32_e32 v130, v134, v130
	v_and_b32_e32 v134, 64, v139
	v_add_u32_e32 v134, 64, v134
	v_xor_b32_e32 v135, 1, v139
	v_cmp_lt_i32_e32 vcc, v135, v134
	s_nop 1
	v_cndmask_b32_e32 v135, v139, v135, vcc
	v_lshlrev_b32_e32 v146, 2, v135
	ds_bpermute_b32 v135, v146, v130
	s_waitcnt lgkmcnt(0)
	v_add_f32_e32 v130, v130, v135
	v_xor_b32_e32 v135, 2, v139
	v_cmp_lt_i32_e32 vcc, v135, v134
	s_nop 1
	v_cndmask_b32_e32 v135, v139, v135, vcc
	v_lshlrev_b32_e32 v147, 2, v135
	ds_bpermute_b32 v135, v147, v130
	s_waitcnt lgkmcnt(0)
	v_add_f32_e32 v130, v130, v135
	v_xor_b32_e32 v135, 4, v139
	v_cmp_lt_i32_e32 vcc, v135, v134
	s_nop 1
	v_cndmask_b32_e32 v135, v139, v135, vcc
	v_lshlrev_b32_e32 v148, 2, v135
	ds_bpermute_b32 v135, v148, v130
	s_waitcnt lgkmcnt(0)
	v_add_f32_e32 v130, v130, v135
	v_xor_b32_e32 v135, 8, v139
	v_cmp_lt_i32_e32 vcc, v135, v134
	s_nop 1
	v_cndmask_b32_e32 v135, v139, v135, vcc
	v_lshlrev_b32_e32 v149, 2, v135
	ds_bpermute_b32 v135, v149, v130
	s_waitcnt lgkmcnt(0)
	v_add_f32_e32 v130, v130, v135
	v_xor_b32_e32 v135, 16, v139
	v_cmp_lt_i32_e32 vcc, v135, v134
	s_nop 1
	v_cndmask_b32_e32 v135, v139, v135, vcc
	v_lshlrev_b32_e32 v150, 2, v135
	ds_bpermute_b32 v135, v150, v130
	s_waitcnt lgkmcnt(0)
	v_add_f32_e32 v130, v130, v135
	v_xor_b32_e32 v135, 32, v139
	v_cmp_lt_i32_e32 vcc, v135, v134
	s_nop 1
	v_cndmask_b32_e32 v134, v139, v135, vcc
	v_lshlrev_b32_e32 v151, 2, v134
	ds_bpermute_b32 v134, v151, v130
	s_waitcnt lgkmcnt(0)
	v_add_f32_e32 v152, v130, v134
	v_fmamk_f32 v127, v152, 0xb9800000, v127
	v_fmamk_f32 v126, v152, 0xb9800000, v126
	v_fmamk_f32 v129, v152, 0xb9800000, v129
	v_fmac_f32_e32 v128, 0xb9800000, v152
	v_pk_mul_f32 v[134:135], v[128:129], v[128:129]
	v_pk_mul_f32 v[140:141], v[126:127], v[126:127]
	v_fmamk_f32 v125, v152, 0xb9800000, v125
	v_pk_mov_b32 v[142:143], v[140:141], v[134:135] op_sel:[1,0]
	v_mov_b32_e32 v141, v135
	v_pk_add_f32 v[134:135], v[142:143], v[140:141]
	v_fmac_f32_e32 v124, 0xb9800000, v152
	v_pk_add_f32 v[140:141], v[134:135], v[134:135] op_sel_hi:[0,1]
	v_fmamk_f32 v135, v152, 0xb9800000, v123
	v_fmamk_f32 v134, v152, 0xb9800000, v122
	v_pk_mul_f32 v[122:123], v[124:125], v[124:125]
	v_pk_mul_f32 v[142:143], v[134:135], v[134:135]
	v_fmac_f32_e32 v120, 0xb9800000, v152
	v_pk_mov_b32 v[144:145], v[142:143], v[122:123] op_sel:[1,0]
	v_mov_b32_e32 v143, v123
	v_pk_add_f32 v[122:123], v[144:145], v[142:143]
	v_fmamk_f32 v121, v152, 0xb9800000, v121
	v_pk_add_f32 v[142:143], v[122:123], v[122:123] op_sel_hi:[0,1]
	v_fmamk_f32 v122, v152, 0xb9800000, v118
	v_fmamk_f32 v123, v152, 0xb9800000, v119
	v_mul_f32_e32 v118, v122, v122
	v_pk_fma_f32 v[118:119], v[122:123], v[122:123], v[118:119] op_sel_hi:[1,1,0]
	v_fmamk_f32 v117, v152, 0xb9800000, v117
	v_mul_f32_e32 v118, v120, v120
	v_pk_fma_f32 v[144:145], v[120:121], v[120:121], v[118:119] op_sel_hi:[1,1,0]
	v_fmamk_f32 v116, v152, 0xb9800000, v116
	v_fmamk_f32 v115, v152, 0xb9800000, v115
	v_fmac_f32_e32 v114, 0xb9800000, v152
	v_mul_f32_e32 v118, v114, v114
	v_mul_f32_e32 v144, v115, v115
	v_mul_f32_e32 v140, v116, v116
	v_mul_f32_e32 v142, v117, v117
	v_pk_add_f32 v[118:119], v[118:119], v[144:145]
	v_pk_add_f32 v[140:141], v[140:141], v[142:143]
	v_fmamk_f32 v113, v152, 0xb9800000, v113
	v_pk_add_f32 v[118:119], v[118:119], v[140:141]
	v_fmac_f32_e32 v112, 0xb9800000, v152
	v_pk_add_f32 v[140:141], v[118:119], v[118:119] op_sel_hi:[0,1]
	v_fmamk_f32 v119, v152, 0xb9800000, v111
	v_fmamk_f32 v118, v152, 0xb9800000, v110
	v_pk_mul_f32 v[110:111], v[112:113], v[112:113]
	v_pk_mul_f32 v[142:143], v[118:119], v[118:119]
	v_fmac_f32_e32 v108, 0xb9800000, v152
	v_pk_mov_b32 v[144:145], v[142:143], v[110:111] op_sel:[1,0]
	v_mov_b32_e32 v143, v111
	v_pk_add_f32 v[110:111], v[144:145], v[142:143]
	v_fmamk_f32 v109, v152, 0xb9800000, v109
	v_pk_add_f32 v[142:143], v[110:111], v[110:111] op_sel_hi:[0,1]
	v_fmamk_f32 v110, v152, 0xb9800000, v106
	v_fmamk_f32 v111, v152, 0xb9800000, v107
	v_mul_f32_e32 v106, v110, v110
	v_pk_fma_f32 v[106:107], v[110:111], v[110:111], v[106:107] op_sel_hi:[1,1,0]
	v_fmamk_f32 v105, v152, 0xb9800000, v105
	v_mul_f32_e32 v106, v108, v108
	v_pk_fma_f32 v[144:145], v[108:109], v[108:109], v[106:107] op_sel_hi:[1,1,0]
	v_fmamk_f32 v104, v152, 0xb9800000, v104
	v_fmamk_f32 v103, v152, 0xb9800000, v103
	v_fmac_f32_e32 v102, 0xb9800000, v152
	v_mul_f32_e32 v106, v102, v102
	v_mul_f32_e32 v144, v103, v103
	v_mul_f32_e32 v142, v104, v104
	v_mul_f32_e32 v140, v105, v105
	v_pk_add_f32 v[106:107], v[106:107], v[144:145]
	v_pk_add_f32 v[140:141], v[142:143], v[140:141]
	v_fmamk_f32 v99, v152, 0xb9800000, v99
	v_fmamk_f32 v98, v152, 0xb9800000, v98
	v_fmamk_f32 v101, v152, 0xb9800000, v101
	v_fmac_f32_e32 v100, 0xb9800000, v152
	v_pk_add_f32 v[106:107], v[106:107], v[140:141]
	v_pk_mul_f32 v[140:141], v[100:101], v[100:101]
	v_pk_mul_f32 v[142:143], v[98:99], v[98:99]
	v_fmamk_f32 v30, v152, 0xb9800000, v30
	v_pk_mov_b32 v[144:145], v[142:143], v[140:141] op_sel:[1,0]
	v_mov_b32_e32 v143, v141
	v_fmamk_f32 v31, v152, 0xb9800000, v31
	v_fmac_f32_e32 v32, 0xb9800000, v152
	v_mul_f32_e32 v130, v30, v30
	v_pk_add_f32 v[140:141], v[144:145], v[142:143]
	v_fmamk_f32 v33, v152, 0xb9800000, v33
	v_pk_fma_f32 v[142:143], v[30:31], v[30:31], v[130:131] op_sel_hi:[1,1,0]
	v_mul_f32_e32 v130, v32, v32
	v_pk_fma_f32 v[144:145], v[32:33], v[32:33], v[130:131] op_sel_hi:[1,1,0]
	v_fmamk_f32 v27, v152, 0xb9800000, v27
	v_fmac_f32_e32 v26, 0xb9800000, v152
	v_pk_add_f32 v[106:107], v[106:107], v[106:107] op_sel_hi:[0,1]
	v_pk_add_f32 v[140:141], v[140:141], v[140:141] op_sel_hi:[0,1]
	v_fmamk_f32 v29, v152, 0xb9800000, v29
	v_fmamk_f32 v28, v152, 0xb9800000, v28
	v_mul_f32_e32 v142, v26, v26
	v_mul_f32_e32 v144, v27, v27
	v_mul_f32_e32 v140, v28, v28
	v_mul_f32_e32 v106, v29, v29
	v_pk_add_f32 v[142:143], v[142:143], v[144:145]
	v_pk_add_f32 v[106:107], v[140:141], v[106:107]
	v_fmamk_f32 v23, v152, 0xb9800000, v23
	v_fmamk_f32 v22, v152, 0xb9800000, v22
	v_fmamk_f32 v25, v152, 0xb9800000, v25
	v_fmac_f32_e32 v24, 0xb9800000, v152
	v_pk_add_f32 v[106:107], v[142:143], v[106:107]
	v_pk_mul_f32 v[140:141], v[24:25], v[24:25]
	v_pk_mul_f32 v[142:143], v[22:23], v[22:23]
	v_fmamk_f32 v18, v152, 0xb9800000, v18
	v_pk_mov_b32 v[144:145], v[142:143], v[140:141] op_sel:[1,0]
	v_mov_b32_e32 v143, v141
	v_fmamk_f32 v19, v152, 0xb9800000, v19
	v_fmac_f32_e32 v20, 0xb9800000, v152
	v_mul_f32_e32 v130, v18, v18
	v_pk_add_f32 v[140:141], v[144:145], v[142:143]
	v_fmamk_f32 v21, v152, 0xb9800000, v21
	v_pk_fma_f32 v[142:143], v[18:19], v[18:19], v[130:131] op_sel_hi:[1,1,0]
	v_mul_f32_e32 v130, v20, v20
	v_pk_fma_f32 v[144:145], v[20:21], v[20:21], v[130:131] op_sel_hi:[1,1,0]
	v_fmamk_f32 v15, v152, 0xb9800000, v15
	v_fmac_f32_e32 v14, 0xb9800000, v152
	v_pk_add_f32 v[106:107], v[106:107], v[106:107] op_sel_hi:[0,1]
	v_pk_add_f32 v[140:141], v[140:141], v[140:141] op_sel_hi:[0,1]
	v_fmamk_f32 v17, v152, 0xb9800000, v17
	v_fmamk_f32 v16, v152, 0xb9800000, v16
	v_mul_f32_e32 v142, v14, v14
	v_mul_f32_e32 v144, v15, v15
	v_mul_f32_e32 v140, v16, v16
	v_mul_f32_e32 v106, v17, v17
	v_pk_add_f32 v[142:143], v[142:143], v[144:145]
	v_pk_add_f32 v[106:107], v[140:141], v[106:107]
	v_fmamk_f32 v11, v152, 0xb9800000, v11
	v_fmamk_f32 v10, v152, 0xb9800000, v10
	v_fmamk_f32 v13, v152, 0xb9800000, v13
	v_fmac_f32_e32 v12, 0xb9800000, v152
	v_pk_add_f32 v[106:107], v[142:143], v[106:107]
	v_pk_mul_f32 v[140:141], v[12:13], v[12:13]
	v_pk_mul_f32 v[142:143], v[10:11], v[10:11]
	v_fmamk_f32 v6, v152, 0xb9800000, v6
	v_pk_mov_b32 v[144:145], v[142:143], v[140:141] op_sel:[1,0]
	v_mov_b32_e32 v143, v141
	v_fmamk_f32 v7, v152, 0xb9800000, v7
	v_fmac_f32_e32 v8, 0xb9800000, v152
	v_mul_f32_e32 v130, v6, v6
	v_pk_add_f32 v[140:141], v[144:145], v[142:143]
	v_fmamk_f32 v9, v152, 0xb9800000, v9
	v_pk_fma_f32 v[142:143], v[6:7], v[6:7], v[130:131] op_sel_hi:[1,1,0]
	v_mul_f32_e32 v130, v8, v8
	v_pk_fma_f32 v[144:145], v[8:9], v[8:9], v[130:131] op_sel_hi:[1,1,0]
	v_fmamk_f32 v3, v152, 0xb9800000, v3
	v_fmac_f32_e32 v2, 0xb9800000, v152
	v_fmamk_f32 v5, v152, 0xb9800000, v5
	v_fmamk_f32 v4, v152, 0xb9800000, v4
	v_pk_add_f32 v[106:107], v[106:107], v[106:107] op_sel_hi:[0,1]
	v_pk_add_f32 v[140:141], v[140:141], v[140:141] op_sel_hi:[0,1]
	v_mul_f32_e32 v142, v2, v2
	v_mul_f32_e32 v144, v3, v3
	v_mul_f32_e32 v140, v4, v4
	v_mul_f32_e32 v106, v5, v5
	v_pk_add_f32 v[142:143], v[142:143], v[144:145]
	v_pk_add_f32 v[106:107], v[140:141], v[106:107]
	s_nop 0
	v_pk_add_f32 v[106:107], v[142:143], v[106:107]
	s_nop 0
	v_add_f32_e32 v106, v106, v107
	ds_bpermute_b32 v107, v146, v106
	s_waitcnt lgkmcnt(0)
	v_add_f32_e32 v106, v106, v107
	ds_bpermute_b32 v107, v147, v106
	s_waitcnt lgkmcnt(0)
	v_add_f32_e32 v106, v106, v107
	ds_bpermute_b32 v107, v148, v106
	s_waitcnt lgkmcnt(0)
	v_add_f32_e32 v106, v106, v107
	ds_bpermute_b32 v107, v149, v106
	s_waitcnt lgkmcnt(0)
	v_add_f32_e32 v106, v106, v107
	ds_bpermute_b32 v107, v150, v106
	s_waitcnt lgkmcnt(0)
	v_add_f32_e32 v106, v106, v107
	ds_bpermute_b32 v107, v151, v106
	s_waitcnt lgkmcnt(0)
	v_add_f32_e32 v106, v106, v107
	v_fmamk_f32 v106, v106, 0x39800000, v137
	v_mul_f32_e32 v107, 0x4f800000, v106
	v_cmp_gt_f32_e32 vcc, s12, v106
	s_nop 1
	v_cndmask_b32_e32 v106, v106, v107, vcc
	v_sqrt_f32_e32 v107, v106
	s_nop 0
	v_add_u32_e32 v130, -1, v107
	v_fma_f32 v140, -v130, v107, v106
	v_cmp_ge_f32_e64 s[0:1], 0, v140
	v_add_u32_e32 v140, 1, v107
	s_nop 0
	v_cndmask_b32_e64 v130, v107, v130, s[0:1]
	v_fma_f32 v107, -v140, v107, v106
	v_cmp_lt_f32_e64 s[0:1], 0, v107
	s_nop 1
	v_cndmask_b32_e64 v107, v130, v140, s[0:1]
	v_mul_f32_e32 v130, 0x37800000, v107
	v_cndmask_b32_e32 v107, v107, v130, vcc
	v_cmp_class_f32_e32 vcc, v106, v138
	s_nop 1
	v_cndmask_b32_e32 v106, v107, v106, vcc
	v_div_scale_f32 v107, s[0:1], v106, v106, 1.0
	v_rcp_f32_e32 v130, v107
	s_and_b32 s0, s6, 0xffff8000
	s_add_i32 s0, s0, 0xfffc8000
	s_cmpk_gt_i32 s8, 0x1fff
	v_fma_f32 v140, -v107, v130, 1.0
	v_fmac_f32_e32 v130, v140, v130
	v_div_scale_f32 v140, vcc, 1.0, v106, 1.0
	v_mul_f32_e32 v141, v140, v130
	v_fma_f32 v142, -v107, v141, v140
	v_fmac_f32_e32 v141, v142, v130
	v_fma_f32 v107, -v107, v141, v140
	s_cselect_b32 s0, s0, 0
	v_div_fmas_f32 v107, v107, v130, v141
	v_add_u32_e32 v130, s0, v136
	ds_read_b128 v[140:143], v130 offset:49152
	ds_read_b128 v[144:147], v130 offset:32768
	ds_read_b128 v[148:151], v130 offset:50176
	v_div_fixup_f32 v106, v107, v106, 1.0
	v_pk_mul_f32 v[128:129], v[128:129], v[106:107] op_sel_hi:[1,0]
	v_pk_mul_f32 v[126:127], v[126:127], v[106:107] op_sel_hi:[1,0]
	s_waitcnt lgkmcnt(2)
	v_pk_add_f32 v[152:153], v[142:143], 1.0 op_sel_hi:[1,0]
	v_pk_add_f32 v[154:155], v[140:141], 1.0 op_sel_hi:[1,0]
	ds_read_b128 v[140:143], v130 offset:33792
	s_waitcnt lgkmcnt(2)
	v_pk_fma_f32 v[128:129], v[152:153], v[128:129], v[146:147]
	v_pk_fma_f32 v[152:153], v[154:155], v[126:127], v[144:145]
	v_pk_mul_f32 v[124:125], v[124:125], v[106:107] op_sel_hi:[1,0]
	s_waitcnt lgkmcnt(1)
	v_pk_add_f32 v[126:127], v[150:151], 1.0 op_sel_hi:[1,0]
	v_pk_add_f32 v[144:145], v[148:149], 1.0 op_sel_hi:[1,0]
	s_waitcnt lgkmcnt(0)
	v_pk_fma_f32 v[148:149], v[126:127], v[124:125], v[142:143]
	v_pk_mul_f32 v[134:135], v[134:135], v[106:107] op_sel_hi:[1,0]
	ds_read_b128 v[124:127], v130 offset:51200
	v_pk_fma_f32 v[134:135], v[144:145], v[134:135], v[140:141]
	ds_read_b128 v[140:143], v130 offset:52224
	ds_read_b128 v[144:147], v130 offset:34816
	v_pk_mul_f32 v[120:121], v[120:121], v[106:107] op_sel_hi:[1,0]
	v_pk_mul_f32 v[122:123], v[122:123], v[106:107] op_sel_hi:[1,0]
	v_mov_b32_e32 v107, 0
	v_cvt_pk_fp8_f32 v107, v152, v153
	s_waitcnt lgkmcnt(2)
	v_pk_add_f32 v[154:155], v[124:125], 1.0 op_sel_hi:[1,0]
	v_pk_add_f32 v[150:151], v[126:127], 1.0 op_sel_hi:[1,0]
	s_waitcnt lgkmcnt(0)
	v_pk_fma_f32 v[122:123], v[154:155], v[122:123], v[144:145]
	v_mov_b32_e32 v144, 0
	v_cvt_pk_fp8_f32 v144, v134, v135
	v_mov_b32_e32 v134, 0
	ds_read_b128 v[124:127], v130 offset:35840
	v_cvt_pk_fp8_f32 v134, v122, v123
	v_cvt_pk_fp8_f32 v107, v128, v129 op_sel:[0,0,1]
	v_pk_fma_f32 v[120:121], v[150:151], v[120:121], v[146:147]
	v_cvt_pk_fp8_f32 v144, v148, v149 op_sel:[0,0,1]
	v_cvt_pk_fp8_f32 v134, v120, v121 op_sel:[0,0,1]
	v_pk_mul_f32 v[114:115], v[114:115], v[106:107] op_sel_hi:[1,0]
	v_pk_add_f32 v[120:121], v[140:141], 1.0 op_sel_hi:[1,0]
	v_pk_mul_f32 v[118:119], v[118:119], v[106:107] op_sel_hi:[1,0]
	s_waitcnt lgkmcnt(0)
	v_pk_fma_f32 v[114:115], v[120:121], v[114:115], v[124:125]
	v_mov_b32_e32 v120, 0
	v_cvt_pk_fp8_f32 v120, v114, v115
	v_pk_mul_f32 v[114:115], v[116:117], v[106:107] op_sel_hi:[1,0]
	v_pk_add_f32 v[116:117], v[142:143], 1.0 op_sel_hi:[1,0]
	s_add_i32 s6, s6, s7
	v_pk_fma_f32 v[114:115], v[116:117], v[114:115], v[126:127]
	s_andn2_b64 vcc, exec, s[4:5]
	v_cvt_pk_fp8_f32 v120, v114, v115 op_sel:[0,0,1]
	v_bfe_u32 v170, v132, 2, 2
	v_mul_u32_u24_e32 v170, 0xfc, v170
	v_mov_b32_e32 v171, 0
	s_nop 0
	v_lshl_add_u64 v[168:169], v[132:133], 0, v[170:171]
	s_mov_b64 s[100:101], vcc
	s_mov_b32 vcc_lo, 0x55555555
	s_mov_b32 vcc_hi, 0x55555555
	v_cndmask_b32_dpp v164, v144, v107, vcc quad_perm:[0,0,2,2] row_mask:0xf bank_mask:0xf
	v_cndmask_b32_dpp v166, v120, v134, vcc quad_perm:[0,0,2,2] row_mask:0xf bank_mask:0xf
	s_mov_b32 vcc_lo, 0xaaaaaaaa
	s_mov_b32 vcc_hi, 0xaaaaaaaa
	v_cndmask_b32_dpp v165, v107, v144, vcc quad_perm:[1,1,3,3] row_mask:0xf bank_mask:0xf
	v_cndmask_b32_dpp v167, v134, v120, vcc quad_perm:[1,1,3,3] row_mask:0xf bank_mask:0xf
	s_mov_b32 vcc_lo, 0x33333333
	s_mov_b32 vcc_hi, 0x33333333
	s_nop 1
	v_cndmask_b32_dpp v160, v166, v164, vcc quad_perm:[0,1,0,1] row_mask:0xf bank_mask:0xf
	v_cndmask_b32_dpp v161, v167, v165, vcc quad_perm:[0,1,0,1] row_mask:0xf bank_mask:0xf
	s_mov_b32 vcc_lo, 0xcccccccc
	s_mov_b32 vcc_hi, 0xcccccccc
	v_cndmask_b32_dpp v162, v164, v166, vcc quad_perm:[2,3,2,3] row_mask:0xf bank_mask:0xf
	v_cndmask_b32_dpp v163, v165, v167, vcc quad_perm:[2,3,2,3] row_mask:0xf bank_mask:0xf
	s_mov_b64 vcc, s[100:101]
	global_store_dwordx4 v[168:169], v[160:163], off sc1
	ds_read_b128 v[114:117], v130 offset:53248
	ds_read_b128 v[120:123], v130 offset:36864
	v_mov_b32_e32 v107, 0
	ds_read_b128 v[124:127], v130 offset:54272
	ds_read_b128 v[140:143], v130 offset:37888
	s_waitcnt lgkmcnt(3)
	v_pk_add_f32 v[114:115], v[114:115], 1.0 op_sel_hi:[1,0]
	s_mov_b32 s8, s13
	s_waitcnt lgkmcnt(2)
	v_pk_fma_f32 v[114:115], v[114:115], v[118:119], v[120:121]
	s_nop 0
	v_cvt_pk_fp8_f32 v107, v114, v115
	v_pk_add_f32 v[114:115], v[116:117], 1.0 op_sel_hi:[1,0]
	ds_read_b128 v[116:119], v130 offset:56320
	v_pk_mul_f32 v[112:113], v[112:113], v[106:107] op_sel_hi:[1,0]
	s_nop 0
	v_pk_fma_f32 v[112:113], v[114:115], v[112:113], v[122:123]
	ds_read_b128 v[120:123], v130 offset:39936
	v_cvt_pk_fp8_f32 v107, v112, v113 op_sel:[0,0,1]
	s_waitcnt lgkmcnt(3)
	v_pk_add_f32 v[112:113], v[124:125], 1.0 op_sel_hi:[1,0]
	v_mov_b32_e32 v124, 0
	v_pk_mul_f32 v[110:111], v[110:111], v[106:107] op_sel_hi:[1,0]
	s_waitcnt lgkmcnt(2)
	v_pk_fma_f32 v[110:111], v[112:113], v[110:111], v[140:141]
	v_pk_mul_f32 v[108:109], v[108:109], v[106:107] op_sel_hi:[1,0]
	v_cvt_pk_fp8_f32 v124, v110, v111
	v_pk_add_f32 v[110:111], v[126:127], 1.0 op_sel_hi:[1,0]
	v_pk_mul_f32 v[102:103], v[102:103], v[106:107] op_sel_hi:[1,0]
	v_pk_fma_f32 v[112:113], v[110:111], v[108:109], v[142:143]
	ds_read_b128 v[108:111], v130 offset:55296
	v_cvt_pk_fp8_f32 v124, v112, v113 op_sel:[0,0,1]
	ds_read_b128 v[112:115], v130 offset:38912
	v_pk_mul_f32 v[98:99], v[98:99], v[106:107] op_sel_hi:[1,0]
	v_pk_mul_f32 v[30:31], v[30:31], v[106:107] op_sel_hi:[1,0]
	s_waitcnt lgkmcnt(1)
	v_pk_add_f32 v[108:109], v[108:109], 1.0 op_sel_hi:[1,0]
	s_waitcnt vmcnt(16)
	v_mov_b64_e32 v[128:129], v[48:49]
	s_waitcnt lgkmcnt(0)
	v_pk_fma_f32 v[102:103], v[102:103], v[108:109], v[112:113]
	v_mov_b32_e32 v108, 0
	v_cvt_pk_fp8_f32 v108, v102, v103
	v_pk_mul_f32 v[102:103], v[104:105], v[106:107] op_sel_hi:[1,0]
	v_pk_add_f32 v[104:105], v[110:111], 1.0 op_sel_hi:[1,0]
	v_mov_b64_e32 v[126:127], v[46:47]
	v_pk_fma_f32 v[102:103], v[102:103], v[104:105], v[114:115]
	s_nop 0
	v_cvt_pk_fp8_f32 v108, v102, v103 op_sel:[0,0,1]
	v_pk_add_f32 v[102:103], v[116:117], 1.0 op_sel_hi:[1,0]
	s_nop 0
	v_pk_fma_f32 v[98:99], v[98:99], v[102:103], v[120:121]
	v_mov_b32_e32 v102, 0
	v_cvt_pk_fp8_f32 v102, v98, v99
	v_pk_mul_f32 v[98:99], v[100:101], v[106:107] op_sel_hi:[1,0]
	v_pk_add_f32 v[100:101], v[118:119], 1.0 op_sel_hi:[1,0]
	s_waitcnt vmcnt(14)
	v_mov_b64_e32 v[120:121], v[40:41]
	v_pk_fma_f32 v[98:99], v[98:99], v[100:101], v[122:123]
	v_mov_b64_e32 v[118:119], v[38:39]
	v_cvt_pk_fp8_f32 v102, v98, v99 op_sel:[0,0,1]
	v_bfe_u32 v170, v132, 2, 2
	v_mul_u32_u24_e32 v170, 0xfc, v170
	v_mov_b32_e32 v171, 0
	s_nop 0
	v_lshl_add_u64 v[168:169], v[132:133], 0, v[170:171]
	s_mov_b64 s[100:101], vcc
	s_mov_b32 vcc_lo, 0x55555555
	s_mov_b32 vcc_hi, 0x55555555
	v_cndmask_b32_dpp v164, v124, v107, vcc quad_perm:[0,0,2,2] row_mask:0xf bank_mask:0xf
	v_cndmask_b32_dpp v166, v102, v108, vcc quad_perm:[0,0,2,2] row_mask:0xf bank_mask:0xf
	s_mov_b32 vcc_lo, 0xaaaaaaaa
	s_mov_b32 vcc_hi, 0xaaaaaaaa
	v_cndmask_b32_dpp v165, v107, v124, vcc quad_perm:[1,1,3,3] row_mask:0xf bank_mask:0xf
	v_cndmask_b32_dpp v167, v108, v102, vcc quad_perm:[1,1,3,3] row_mask:0xf bank_mask:0xf
	s_mov_b32 vcc_lo, 0x33333333
	s_mov_b32 vcc_hi, 0x33333333
	s_nop 1
	v_cndmask_b32_dpp v160, v166, v164, vcc quad_perm:[0,1,0,1] row_mask:0xf bank_mask:0xf
	v_cndmask_b32_dpp v161, v167, v165, vcc quad_perm:[0,1,0,1] row_mask:0xf bank_mask:0xf
	s_mov_b32 vcc_lo, 0xcccccccc
	s_mov_b32 vcc_hi, 0xcccccccc
	v_cndmask_b32_dpp v162, v164, v166, vcc quad_perm:[2,3,2,3] row_mask:0xf bank_mask:0xf
	v_cndmask_b32_dpp v163, v165, v167, vcc quad_perm:[2,3,2,3] row_mask:0xf bank_mask:0xf
	s_mov_b64 vcc, s[100:101]
	global_store_dwordx4 v[168:169], v[160:163], off offset:1024 sc1
	ds_read_b128 v[98:101], v130 offset:57344
	ds_read_b128 v[102:105], v130 offset:40960
	v_mov_b32_e32 v107, 0
	ds_read_b128 v[108:111], v130 offset:58368
	ds_read_b128 v[112:115], v130 offset:41984
	s_waitcnt lgkmcnt(3)
	v_pk_add_f32 v[98:99], v[98:99], 1.0 op_sel_hi:[1,0]
	v_mov_b64_e32 v[124:125], v[44:45]
	s_waitcnt lgkmcnt(2)
	v_pk_fma_f32 v[30:31], v[30:31], v[98:99], v[102:103]
	v_mov_b64_e32 v[122:123], v[42:43]
	v_cvt_pk_fp8_f32 v107, v30, v31
	v_pk_mul_f32 v[30:31], v[32:33], v[106:107] op_sel_hi:[1,0]
	v_pk_add_f32 v[32:33], v[100:101], 1.0 op_sel_hi:[1,0]
	ds_read_b128 v[98:101], v130 offset:60416
	v_pk_fma_f32 v[30:31], v[30:31], v[32:33], v[104:105]
	ds_read_b128 v[102:105], v130 offset:44032
	v_cvt_pk_fp8_f32 v107, v30, v31 op_sel:[0,0,1]
	s_waitcnt lgkmcnt(3)
	v_pk_add_f32 v[30:31], v[108:109], 1.0 op_sel_hi:[1,0]
	v_mov_b32_e32 v108, 0
	v_pk_mul_f32 v[26:27], v[26:27], v[106:107] op_sel_hi:[1,0]
	s_waitcnt lgkmcnt(2)
	v_pk_fma_f32 v[26:27], v[26:27], v[30:31], v[112:113]
	v_pk_mul_f32 v[28:29], v[28:29], v[106:107] op_sel_hi:[1,0]
	v_cvt_pk_fp8_f32 v108, v26, v27
	v_pk_add_f32 v[26:27], v[110:111], 1.0 op_sel_hi:[1,0]
	v_pk_mul_f32 v[22:23], v[22:23], v[106:107] op_sel_hi:[1,0]
	v_pk_fma_f32 v[30:31], v[28:29], v[26:27], v[114:115]
	ds_read_b128 v[26:29], v130 offset:59392
	v_cvt_pk_fp8_f32 v108, v30, v31 op_sel:[0,0,1]
	ds_read_b128 v[30:33], v130 offset:43008
	v_pk_mul_f32 v[18:19], v[18:19], v[106:107] op_sel_hi:[1,0]
	v_pk_mul_f32 v[14:15], v[14:15], v[106:107] op_sel_hi:[1,0]
	s_waitcnt lgkmcnt(1)
	v_pk_add_f32 v[26:27], v[26:27], 1.0 op_sel_hi:[1,0]
	v_pk_mul_f32 v[10:11], v[10:11], v[106:107] op_sel_hi:[1,0]
	s_waitcnt lgkmcnt(0)
	v_pk_fma_f32 v[22:23], v[22:23], v[26:27], v[30:31]
	v_mov_b32_e32 v26, 0
	v_cvt_pk_fp8_f32 v26, v22, v23
	v_pk_mul_f32 v[22:23], v[24:25], v[106:107] op_sel_hi:[1,0]
	v_pk_add_f32 v[24:25], v[28:29], 1.0 op_sel_hi:[1,0]
	v_pk_mul_f32 v[12:13], v[12:13], v[106:107] op_sel_hi:[1,0]
	v_pk_fma_f32 v[22:23], v[22:23], v[24:25], v[32:33]
	v_pk_mul_f32 v[6:7], v[6:7], v[106:107] op_sel_hi:[1,0]
	v_cvt_pk_fp8_f32 v26, v22, v23 op_sel:[0,0,1]
	v_pk_add_f32 v[22:23], v[98:99], 1.0 op_sel_hi:[1,0]
	v_mov_b32_e32 v98, 0
	v_pk_fma_f32 v[18:19], v[18:19], v[22:23], v[102:103]
	v_mov_b32_e32 v22, 0
	v_cvt_pk_fp8_f32 v22, v18, v19
	v_pk_mul_f32 v[18:19], v[20:21], v[106:107] op_sel_hi:[1,0]
	v_pk_add_f32 v[20:21], v[100:101], 1.0 op_sel_hi:[1,0]
	v_pk_mul_f32 v[2:3], v[2:3], v[106:107] op_sel_hi:[1,0]
	v_pk_fma_f32 v[18:19], v[18:19], v[20:21], v[104:105]
	s_waitcnt vmcnt(14)
	v_mov_b64_e32 v[116:117], v[36:37]
	v_cvt_pk_fp8_f32 v22, v18, v19 op_sel:[0,0,1]
	v_bfe_u32 v170, v132, 2, 2
	v_mul_u32_u24_e32 v170, 0xfc, v170
	v_mov_b32_e32 v171, 0
	s_nop 0
	v_lshl_add_u64 v[168:169], v[132:133], 0, v[170:171]
	s_mov_b64 s[100:101], vcc
	s_mov_b32 vcc_lo, 0x55555555
	s_mov_b32 vcc_hi, 0x55555555
	v_cndmask_b32_dpp v164, v108, v107, vcc quad_perm:[0,0,2,2] row_mask:0xf bank_mask:0xf
	v_cndmask_b32_dpp v166, v22, v26, vcc quad_perm:[0,0,2,2] row_mask:0xf bank_mask:0xf
	s_mov_b32 vcc_lo, 0xaaaaaaaa
	s_mov_b32 vcc_hi, 0xaaaaaaaa
	v_cndmask_b32_dpp v165, v107, v108, vcc quad_perm:[1,1,3,3] row_mask:0xf bank_mask:0xf
	v_cndmask_b32_dpp v167, v26, v22, vcc quad_perm:[1,1,3,3] row_mask:0xf bank_mask:0xf
	s_mov_b32 vcc_lo, 0x33333333
	s_mov_b32 vcc_hi, 0x33333333
	s_nop 1
	v_cndmask_b32_dpp v160, v166, v164, vcc quad_perm:[0,1,0,1] row_mask:0xf bank_mask:0xf
	v_cndmask_b32_dpp v161, v167, v165, vcc quad_perm:[0,1,0,1] row_mask:0xf bank_mask:0xf
	s_mov_b32 vcc_lo, 0xcccccccc
	s_mov_b32 vcc_hi, 0xcccccccc
	v_cndmask_b32_dpp v162, v164, v166, vcc quad_perm:[2,3,2,3] row_mask:0xf bank_mask:0xf
	v_cndmask_b32_dpp v163, v165, v167, vcc quad_perm:[2,3,2,3] row_mask:0xf bank_mask:0xf
	s_mov_b64 vcc, s[100:101]
	global_store_dwordx4 v[168:169], v[160:163], off offset:2048 sc1
	ds_read_b128 v[18:21], v130 offset:61440
	ds_read_b128 v[22:25], v130 offset:45056
	ds_read_b128 v[26:29], v130 offset:62464
	ds_read_b128 v[30:33], v130 offset:46080
	s_waitcnt vmcnt(14)
	v_mov_b64_e32 v[112:113], v[64:65]
	s_waitcnt lgkmcnt(3)
	v_pk_add_f32 v[18:19], v[18:19], 1.0 op_sel_hi:[1,0]
	s_waitcnt vmcnt(12)
	v_mov_b64_e32 v[104:105], v[56:57]
	s_waitcnt lgkmcnt(2)
	v_pk_fma_f32 v[14:15], v[14:15], v[18:19], v[22:23]
	v_mov_b64_e32 v[114:115], v[34:35]
	v_cvt_pk_fp8_f32 v98, v14, v15
	v_pk_mul_f32 v[14:15], v[16:17], v[106:107] op_sel_hi:[1,0]
	v_pk_add_f32 v[16:17], v[20:21], 1.0 op_sel_hi:[1,0]
	ds_read_b128 v[18:21], v130 offset:64512
	v_pk_fma_f32 v[14:15], v[14:15], v[16:17], v[24:25]
	ds_read_b128 v[22:25], v130 offset:48128
	v_cvt_pk_fp8_f32 v98, v14, v15 op_sel:[0,0,1]
	s_waitcnt lgkmcnt(3)
	v_pk_add_f32 v[14:15], v[26:27], 1.0 op_sel_hi:[1,0]
	v_mov_b32_e32 v26, 0
	s_waitcnt lgkmcnt(2)
	v_pk_fma_f32 v[10:11], v[10:11], v[14:15], v[30:31]
	v_mov_b64_e32 v[110:111], v[62:63]
	v_cvt_pk_fp8_f32 v26, v10, v11
	v_pk_add_f32 v[10:11], v[28:29], 1.0 op_sel_hi:[1,0]
	v_mov_b64_e32 v[102:103], v[54:55]
	v_pk_fma_f32 v[14:15], v[12:13], v[10:11], v[32:33]
	ds_read_b128 v[10:13], v130 offset:63488
	v_cvt_pk_fp8_f32 v26, v14, v15 op_sel:[0,0,1]
	ds_read_b128 v[14:17], v130 offset:47104
	s_waitcnt vmcnt(10)
	v_mov_b64_e32 v[30:31], v[78:79]
	v_mov_b64_e32 v[32:33], v[80:81]
	s_waitcnt lgkmcnt(1)
	v_pk_add_f32 v[10:11], v[10:11], 1.0 op_sel_hi:[1,0]
	s_waitcnt lgkmcnt(0)
	v_pk_fma_f32 v[6:7], v[6:7], v[10:11], v[14:15]
	v_mov_b32_e32 v10, 0
	v_cvt_pk_fp8_f32 v10, v6, v7
	v_pk_mul_f32 v[6:7], v[8:9], v[106:107] op_sel_hi:[1,0]
	v_pk_add_f32 v[8:9], v[12:13], 1.0 op_sel_hi:[1,0]
	s_nop 0
	v_pk_fma_f32 v[6:7], v[6:7], v[8:9], v[16:17]
	s_waitcnt vmcnt(6)
	v_mov_b64_e32 v[14:15], v[94:95]
	v_cvt_pk_fp8_f32 v10, v6, v7 op_sel:[0,0,1]
	v_pk_add_f32 v[6:7], v[18:19], 1.0 op_sel_hi:[1,0]
	v_mov_b64_e32 v[16:17], v[96:97]
	v_pk_fma_f32 v[2:3], v[2:3], v[6:7], v[22:23]
	v_mov_b32_e32 v6, 0
	v_cvt_pk_fp8_f32 v6, v2, v3
	v_pk_mul_f32 v[2:3], v[4:5], v[106:107] op_sel_hi:[1,0]
	v_pk_add_f32 v[4:5], v[20:21], 1.0 op_sel_hi:[1,0]
	v_mov_b64_e32 v[108:109], v[60:61]
	v_pk_fma_f32 v[2:3], v[2:3], v[4:5], v[24:25]
	v_mov_b64_e32 v[22:23], v[70:71]
	v_cvt_pk_fp8_f32 v6, v2, v3 op_sel:[0,0,1]
	v_bfe_u32 v170, v132, 2, 2
	v_mul_u32_u24_e32 v170, 0xfc, v170
	v_mov_b32_e32 v171, 0
	s_nop 0
	v_lshl_add_u64 v[168:169], v[132:133], 0, v[170:171]
	s_mov_b64 s[100:101], vcc
	s_mov_b32 vcc_lo, 0x55555555
	s_mov_b32 vcc_hi, 0x55555555
	v_cndmask_b32_dpp v164, v26, v98, vcc quad_perm:[0,0,2,2] row_mask:0xf bank_mask:0xf
	v_cndmask_b32_dpp v166, v6, v10, vcc quad_perm:[0,0,2,2] row_mask:0xf bank_mask:0xf
	s_mov_b32 vcc_lo, 0xaaaaaaaa
	s_mov_b32 vcc_hi, 0xaaaaaaaa
	v_cndmask_b32_dpp v165, v98, v26, vcc quad_perm:[1,1,3,3] row_mask:0xf bank_mask:0xf
	v_cndmask_b32_dpp v167, v10, v6, vcc quad_perm:[1,1,3,3] row_mask:0xf bank_mask:0xf
	s_mov_b32 vcc_lo, 0x33333333
	s_mov_b32 vcc_hi, 0x33333333
	s_nop 1
	v_cndmask_b32_dpp v160, v166, v164, vcc quad_perm:[0,1,0,1] row_mask:0xf bank_mask:0xf
	v_cndmask_b32_dpp v161, v167, v165, vcc quad_perm:[0,1,0,1] row_mask:0xf bank_mask:0xf
	s_mov_b32 vcc_lo, 0xcccccccc
	s_mov_b32 vcc_hi, 0xcccccccc
	v_cndmask_b32_dpp v162, v164, v166, vcc quad_perm:[2,3,2,3] row_mask:0xf bank_mask:0xf
	v_cndmask_b32_dpp v163, v165, v167, vcc quad_perm:[2,3,2,3] row_mask:0xf bank_mask:0xf
	s_mov_b64 vcc, s[100:101]
	global_store_dwordx4 v[168:169], v[160:163], off offset:3072 sc1
	v_mov_b64_e32 v[100:101], v[52:53]
	v_mov_b64_e32 v[26:27], v[74:75]
	v_mov_b64_e32 v[18:19], v[66:67]
	s_waitcnt vmcnt(6)
	v_mov_b64_e32 v[10:11], v[90:91]
	s_waitcnt vmcnt(5)
	v_mov_b64_e32 v[6:7], v[86:87]
	s_waitcnt vmcnt(4)
	v_mov_b64_e32 v[2:3], v[82:83]
	v_lshl_add_u64 v[132:133], v[132:133], 0, s[2:3]
	v_mov_b64_e32 v[106:107], v[58:59]
	v_mov_b64_e32 v[98:99], v[50:51]
	v_mov_b64_e32 v[28:29], v[76:77]
	v_mov_b64_e32 v[24:25], v[72:73]
	v_mov_b64_e32 v[20:21], v[68:69]
	v_mov_b64_e32 v[12:13], v[92:93]
	v_mov_b64_e32 v[8:9], v[88:89]
	v_mov_b64_e32 v[4:5], v[84:85]
	s_cbranch_vccz .LBB0_134
